# placement pin: 4-byte pad so the down gemm loop head sits on an 8-byte phase, on top of v39
# baseline (speedup 1.0000x reference)
; #define PG8_STAGE(bufoff, gbase, voff) do { _Pragma("unroll") for (int _i = 0; _i < 2; ++_i) \
;         __builtin_amdgcn_global_load_lds((const unsigned*)((const char*)(gbase) + (voff)[_i]), (LAS unsigned*)(lds + (bufoff) + ldsw + _i * 8192), 16, 0, 0); } while (0)
; #define PG8_WAIT_V(n) asm volatile("s_waitcnt vmcnt(" #n ")" ::: "memory")
; #define PG8_BAR __builtin_amdgcn_s_barrier()
; template <class Epi, class Addr>
; __device__ __forceinline__ void gemm_phase(LAS unsigned char* lds, const Gemm g, const StaticOrder& S, const Addr& AD, const Epi& E) {
;     ...
;     Acc acc;
; #pragma unroll
;     for (int a = 0; a < 2; ++a)
; #pragma unroll
;         for (int b = 0; b < 2; ++b)
; #pragma unroll
;             for (int m = 0; m < 4; ++m)
; #pragma unroll
;                 for (int n = 0; n < 2; ++n) acc[a][b][m][n] = (f32x4){0.f, 0.f, 0.f, 0.f};
;     bf16x8 At[4][2], B0[2][2], B1[2][2];
;     const char* cA; const char* cB; AD.get(g, cur, cA, cB);
;     PG8_STAGE(PG8_SB(0, 0), cB, voffB); PG8_STAGE(PG8_SB(0, 1), cB + hstepB, voffB); PG8_STAGE(PG8_SA(0, 0), cA, voffA); PG8_STAGE(PG8_SA(0, 1), cA + hstepA, voffA);
;     if (wr == 1) PG8_BAR;
;     PG8_WAIT_V(2); PG8_BAR;
;     PG8_STAGE(PG8_SB(1, 0), cB + kstep, voffB); PG8_STAGE(PG8_SA(1, 0), cA + kstep, voffA); PG8_STAGE(PG8_SB(1, 1), cB + hstepB + kstep, voffB);
;     PG8_WAIT_V(6); PG8_BAR;
;     for (;;) {
;         const bool has_next = S.next(ui + 1, nxt);
;         const char* nA = cA; const char* nB = cB; if (has_next) AD.get(g, nxt, nA, nB);
;         for (int t = 0; t < nt; t += 2) {
.LBB0_1330:
	v_mov_b32_e32 v189, 0
	s_andn2_b64 vcc, exec, s[58:59]
	v_mov_b32_e32 v188, 0
	v_mov_b32_e32 v227, 0
	v_mov_b32_e32 v226, 0
	v_mov_b32_e32 v197, 0
	v_mov_b32_e32 v196, 0
	v_mov_b32_e32 v195, 0
	v_mov_b32_e32 v194, 0
	v_mov_b32_e32 v185, 0
	v_mov_b32_e32 v184, 0
	v_mov_b32_e32 v187, 0
	v_mov_b32_e32 v186, 0
	v_mov_b32_e32 v179, 0
	v_mov_b32_e32 v178, 0
	v_mov_b32_e32 v177, 0
	v_mov_b32_e32 v176, 0
	v_mov_b32_e32 v165, 0
	v_mov_b32_e32 v164, 0
	v_mov_b32_e32 v167, 0
	v_mov_b32_e32 v166, 0
	v_mov_b32_e32 v159, 0
	v_mov_b32_e32 v158, 0
	v_mov_b32_e32 v157, 0
	v_mov_b32_e32 v156, 0
	v_mov_b32_e32 v149, 0
	v_mov_b32_e32 v148, 0
	v_mov_b32_e32 v151, 0
	v_mov_b32_e32 v150, 0
	v_mov_b32_e32 v143, 0
	v_mov_b32_e32 v142, 0
	v_mov_b32_e32 v141, 0
	v_mov_b32_e32 v140, 0
	v_mov_b32_e32 v223, 0
	v_mov_b32_e32 v222, 0
	v_mov_b32_e32 v199, 0
	v_mov_b32_e32 v198, 0
	v_mov_b32_e32 v193, 0
	v_mov_b32_e32 v192, 0
	v_mov_b32_e32 v191, 0
	v_mov_b32_e32 v190, 0
	v_mov_b32_e32 v183, 0
	v_mov_b32_e32 v182, 0
	v_mov_b32_e32 v181, 0
	v_mov_b32_e32 v180, 0
	v_mov_b32_e32 v171, 0
	v_mov_b32_e32 v170, 0
	v_mov_b32_e32 v169, 0
	v_mov_b32_e32 v168, 0
	v_mov_b32_e32 v163, 0
	v_mov_b32_e32 v162, 0
	v_mov_b32_e32 v161, 0
	v_mov_b32_e32 v160, 0
	v_mov_b32_e32 v155, 0
	v_mov_b32_e32 v154, 0
	v_mov_b32_e32 v153, 0
	v_mov_b32_e32 v152, 0
	v_mov_b32_e32 v147, 0
	v_mov_b32_e32 v146, 0
	v_mov_b32_e32 v145, 0
	v_mov_b32_e32 v144, 0
	v_mov_b32_e32 v139, 0
	v_mov_b32_e32 v138, 0
	v_mov_b32_e32 v137, 0
	v_mov_b32_e32 v136, 0
	v_mov_b32_e32 v127, 0
	v_mov_b32_e32 v126, 0
	v_mov_b32_e32 v135, 0
	v_mov_b32_e32 v134, 0
	v_mov_b32_e32 v119, 0
	v_mov_b32_e32 v118, 0
	v_mov_b32_e32 v117, 0
	v_mov_b32_e32 v116, 0
	v_mov_b32_e32 v111, 0
	v_mov_b32_e32 v110, 0
	v_mov_b32_e32 v109, 0
	v_mov_b32_e32 v108, 0
	v_mov_b32_e32 v103, 0
	v_mov_b32_e32 v102, 0
	v_mov_b32_e32 v101, 0
	v_mov_b32_e32 v100, 0
	v_mov_b32_e32 v95, 0
	v_mov_b32_e32 v94, 0
	v_mov_b32_e32 v93, 0
	v_mov_b32_e32 v92, 0
	v_mov_b32_e32 v87, 0
	v_mov_b32_e32 v86, 0
	v_mov_b32_e32 v85, 0
	v_mov_b32_e32 v84, 0
	v_mov_b32_e32 v79, 0
	v_mov_b32_e32 v78, 0
	v_mov_b32_e32 v77, 0
	v_mov_b32_e32 v76, 0
	v_mov_b32_e32 v71, 0
	v_mov_b32_e32 v70, 0
	v_mov_b32_e32 v69, 0
	v_mov_b32_e32 v68, 0
	v_mov_b32_e32 v123, 0
	v_mov_b32_e32 v122, 0
	v_mov_b32_e32 v121, 0
	v_mov_b32_e32 v120, 0
	v_mov_b32_e32 v115, 0
	v_mov_b32_e32 v114, 0
	v_mov_b32_e32 v113, 0
	v_mov_b32_e32 v112, 0
	v_mov_b32_e32 v107, 0
	v_mov_b32_e32 v106, 0
	v_mov_b32_e32 v105, 0
	v_mov_b32_e32 v104, 0
	v_mov_b32_e32 v99, 0
	v_mov_b32_e32 v98, 0
	v_mov_b32_e32 v97, 0
	v_mov_b32_e32 v96, 0
	v_mov_b32_e32 v91, 0
	v_mov_b32_e32 v90, 0
	v_mov_b32_e32 v89, 0
	v_mov_b32_e32 v88, 0
	v_mov_b32_e32 v83, 0
	v_mov_b32_e32 v82, 0
	v_mov_b32_e32 v81, 0
	v_mov_b32_e32 v80, 0
	v_mov_b32_e32 v75, 0
	v_mov_b32_e32 v74, 0
	v_mov_b32_e32 v73, 0
	v_mov_b32_e32 v72, 0
	v_mov_b32_e32 v67, 0
	v_mov_b32_e32 v66, 0
	v_mov_b32_e32 v65, 0
	v_mov_b32_e32 v64, 0
	s_cbranch_vccnz .LBB0_1334
	s_add_u32 s79, s66, 0x100
	v_mov_b32_e32 v0, 0
	s_addc_u32 s80, s67, 0
	s_mov_b32 s66, 0
	s_waitcnt lgkmcnt(0)
	v_mov_b32_e32 v1, v0
	v_mov_b32_e32 v2, v0
	v_mov_b32_e32 v3, v0
	v_mov_b32_e32 v4, v0
	v_mov_b32_e32 v5, v0
	v_mov_b32_e32 v6, v0
	v_mov_b32_e32 v7, v0
	v_mov_b32_e32 v8, v0
	v_mov_b32_e32 v9, v0
	v_mov_b32_e32 v10, v0
	v_mov_b32_e32 v11, v0
	v_mov_b32_e32 v12, v0
	v_mov_b32_e32 v13, v0
	v_mov_b32_e32 v14, v0
	v_mov_b32_e32 v15, v0
	v_mov_b32_e32 v20, v0
	v_mov_b32_e32 v21, v0
	v_mov_b32_e32 v22, v0
	v_mov_b32_e32 v23, v0
	v_mov_b32_e32 v28, v0
	v_mov_b32_e32 v29, v0
	v_mov_b32_e32 v30, v0
	v_mov_b32_e32 v31, v0
	v_mov_b32_e32 v36, v0
	v_mov_b32_e32 v37, v0
	v_mov_b32_e32 v38, v0
	v_mov_b32_e32 v39, v0
	v_mov_b32_e32 v44, v0
	v_mov_b32_e32 v45, v0
	v_mov_b32_e32 v46, v0
	v_mov_b32_e32 v47, v0
	v_mov_b32_e32 v16, v0
	v_mov_b32_e32 v17, v0
	v_mov_b32_e32 v18, v0
	v_mov_b32_e32 v19, v0
	v_mov_b32_e32 v24, v0
	v_mov_b32_e32 v25, v0
	v_mov_b32_e32 v26, v0
	v_mov_b32_e32 v27, v0
	v_mov_b32_e32 v32, v0
	v_mov_b32_e32 v33, v0
	v_mov_b32_e32 v34, v0
	v_mov_b32_e32 v35, v0
	v_mov_b32_e32 v40, v0
	v_mov_b32_e32 v41, v0
	v_mov_b32_e32 v42, v0
	v_mov_b32_e32 v43, v0
	v_mov_b32_e32 v48, v0
	v_mov_b32_e32 v49, v0
	v_mov_b32_e32 v50, v0
	v_mov_b32_e32 v51, v0
	v_mov_b32_e32 v52, v0
	v_mov_b32_e32 v53, v0
	v_mov_b32_e32 v54, v0
	v_mov_b32_e32 v55, v0
	v_mov_b32_e32 v56, v0
	v_mov_b32_e32 v57, v0
	v_mov_b32_e32 v58, v0
	v_mov_b32_e32 v59, v0
	v_mov_b32_e32 v60, v0
	v_mov_b32_e32 v61, v0
	v_mov_b32_e32 v62, v0
	v_mov_b32_e32 v63, v0
	v_mov_b32_e32 v64, v0
	v_mov_b32_e32 v65, v0
	v_mov_b32_e32 v66, v0
	v_mov_b32_e32 v67, v0
	v_mov_b32_e32 v68, v0
	v_mov_b32_e32 v69, v0
	v_mov_b32_e32 v70, v0
	v_mov_b32_e32 v71, v0
	v_mov_b32_e32 v72, v0
	v_mov_b32_e32 v73, v0
	v_mov_b32_e32 v74, v0
	v_mov_b32_e32 v75, v0
	v_mov_b32_e32 v76, v0
	v_mov_b32_e32 v77, v0
	v_mov_b32_e32 v78, v0
	v_mov_b32_e32 v79, v0
	v_mov_b32_e32 v84, v0
	v_mov_b32_e32 v85, v0
	v_mov_b32_e32 v86, v0
	v_mov_b32_e32 v87, v0
	v_mov_b32_e32 v92, v0
	v_mov_b32_e32 v93, v0
	v_mov_b32_e32 v94, v0
	v_mov_b32_e32 v95, v0
	v_mov_b32_e32 v100, v0
	v_mov_b32_e32 v101, v0
	v_mov_b32_e32 v102, v0
	v_mov_b32_e32 v103, v0
	v_mov_b32_e32 v108, v0
	v_mov_b32_e32 v109, v0
	v_mov_b32_e32 v110, v0
	v_mov_b32_e32 v111, v0
	v_mov_b32_e32 v80, v0
	v_mov_b32_e32 v81, v0
	v_mov_b32_e32 v82, v0
	v_mov_b32_e32 v83, v0
	v_mov_b32_e32 v88, v0
	v_mov_b32_e32 v89, v0
	v_mov_b32_e32 v90, v0
	v_mov_b32_e32 v91, v0
	v_mov_b32_e32 v96, v0
	v_mov_b32_e32 v97, v0
	v_mov_b32_e32 v98, v0
	v_mov_b32_e32 v99, v0
	v_mov_b32_e32 v104, v0
	v_mov_b32_e32 v105, v0
	v_mov_b32_e32 v106, v0
	v_mov_b32_e32 v107, v0
	v_mov_b32_e32 v112, v0
	v_mov_b32_e32 v113, v0
	v_mov_b32_e32 v114, v0
	v_mov_b32_e32 v115, v0
	v_mov_b32_e32 v116, v0
	v_mov_b32_e32 v117, v0
	v_mov_b32_e32 v118, v0
	v_mov_b32_e32 v119, v0
	v_mov_b32_e32 v120, v0
	v_mov_b32_e32 v121, v0
	v_mov_b32_e32 v122, v0
	v_mov_b32_e32 v123, v0
	v_mov_b32_e32 v124, v0
	v_mov_b32_e32 v125, v0
	v_mov_b32_e32 v126, v0
	v_mov_b32_e32 v127, v0
	v_add_u32_e32 v198, 0x10000, v242
	v_add_u32_e32 v199, 0x18000, v242
	s_nop 0
